# barrier fence hoist: buffer_inv sc1 issued once right after the arrival atomic (overlapped with its round trip) instead of after the flag flip, all 10 grid barriers
# speedup vs baseline: 1.0194x; 1.0066x over previous
.LBB0_229:
	s_or_b64 exec, exec, s[6:7]
	buffer_inv sc1
	v_cvt_f32_u32_e32 v4, v2
	s_waitcnt vmcnt(0)
	v_readfirstlane_b32 s4, v3
	v_sub_u32_e32 v3, 0, v2
	v_rcp_iflag_f32_e32 v4, v4
	v_add_u32_e32 v5, s4, v1
	v_mul_f32_e32 v4, 0x4f7ffffe, v4
	v_cvt_u32_f32_e32 v4, v4
	v_mul_lo_u32 v1, v3, v4
	v_mul_hi_u32 v1, v4, v1
	v_add_u32_e32 v1, v4, v1
	v_mul_hi_u32 v1, v5, v1
	v_mul_lo_u32 v3, v1, v2
	v_sub_u32_e32 v3, v5, v3
	v_add_u32_e32 v4, 1, v1
	v_cmp_ge_u32_e32 vcc, v3, v2
	s_nop 1
	v_cndmask_b32_e32 v1, v1, v4, vcc
	v_sub_u32_e32 v4, v3, v2
	v_cndmask_b32_e32 v3, v3, v4, vcc
	v_add_u32_e32 v4, 1, v1
	v_cmp_ge_u32_e32 vcc, v3, v2
	v_add_u32_e32 v3, 1, v5
	s_nop 0
	v_cndmask_b32_e32 v1, v1, v4, vcc
	v_mul_lo_u32 v4, v2, v1
	v_add_u32_e32 v2, v4, v2
	v_cmp_ne_u32_e32 vcc, v3, v2
	s_and_saveexec_b64 s[4:5], vcc
	s_xor_b64 s[4:5], exec, s[4:5]
	s_cbranch_execz .LBB0_243
	s_waitcnt lgkmcnt(0)
	v_mov_b32_e32 v0, 0x2000
	global_load_dword v0, v0, s[2:3] offset:1024 sc1
	s_add_u32 s10, s2, 0x2400
	s_addc_u32 s11, s3, 0
	s_waitcnt vmcnt(0)
	v_cmp_eq_u32_e32 vcc, v0, v1
	s_and_saveexec_b64 s[6:7], vcc
	s_cbranch_execz .LBB0_242
	s_add_u32 s8, s84, 0x5900200
	s_addc_u32 s9, s85, 0
	s_mov_b32 s22, 1
	s_mov_b64 s[12:13], 0
	v_mov_b32_e32 v0, 0
	s_branch .LBB0_233

.LBB0_242:
	s_or_b64 exec, exec, s[6:7]
	s_waitcnt vmcnt(0)
	s_waitcnt vmcnt(0)

.LBB0_260:
	s_or_b64 exec, exec, s[4:5]
	s_mov_b64 s[4:5], exec
	v_mbcnt_lo_u32_b32 v0, s4, 0
	v_mbcnt_hi_u32_b32 v0, s5, v0
	v_cmp_eq_u32_e32 vcc, 0, v0
	s_waitcnt vmcnt(0)
	s_and_saveexec_b64 s[6:7], vcc
	s_cbranch_execz .LBB0_262
	s_bcnt1_i32_b64 s4, s[4:5]
	v_mov_b32_e32 v0, 0x2000
	v_mov_b32_e32 v1, s4
	global_atomic_add v0, v1, s[2:3] offset:1024
